# selected-block stream: trimmed softmax VALU (max3, bfe/bfi mask, hoisted LDS lane addresses, in-place exp + packed row sums), counted LDS waits, global loads two stages ahead through SGPR bases
# baseline (speedup 1.0000x reference)
; __device__ __forceinline__ unsigned cvtpk(float lo, float hi) { unsigned r; asm("v_cvt_pk_bf16_f32 %0, %1, %2" : "=v"(r) : "v"(lo), "v"(hi)); return r; }
; __device__ __forceinline__ float col_total(float l) { l += __shfl_xor(l, 16); l += __shfl_xor(l, 32); return l; }
; __device__ __forceinline__ void nsa_block_task(Ctx& C, int task, bf16* ONSA_OUT) {
;     ...
; #pragma unroll
;         for (int cg = 0; cg < 2; ++cg) { const float lt = col_total(a[cg].l); const float sc = lt > 0.f ? g_w[cg] / lt : 0.f;
;         bf16* od = ONSA_OUT + (size_t)tl[cg] * 512 + head * 64 + 4 * fq;
; #pragma unroll
;             for (int c = 0; c < 4; ++c) { const f4 ov = STASH[(cg * 4 + c) * 64 + lane] + a[cg].o[c] * sc;
;                 v2u wv; wv.x = cvtpk(ov[0], ov[1]); wv.y = cvtpk(ov[2], ov[3]); *(v2u*)(od + 16 * c) = wv; } }
.LBB0_1111:
	global_load_dwordx4 v[88:91], v[200:201], off
	global_load_dwordx4 v[92:95], v[200:201], off offset:1024
	global_load_dwordx4 v[96:99], v[200:201], off offset:2048
	global_load_dwordx4 v[100:103], v[200:201], off offset:3072
	global_load_dwordx4 v[104:107], v[202:203], off
	global_load_dwordx4 v[108:111], v[202:203], off offset:1024
	global_load_dwordx4 v[112:115], v[202:203], off offset:2048
	global_load_dwordx4 v[116:119], v[202:203], off offset:3072
	ds_bpermute_b32 v0, v217, v68
	s_waitcnt lgkmcnt(0)
	v_add_f32_e32 v8, v68, v0
	ds_bpermute_b32 v9, v219, v8
	v_lshlrev_b32_e32 v0, 1, v220
	v_lshl_add_u64 v[6:7], v[210:211], 0, v[0:1]
	s_waitcnt lgkmcnt(0)
	v_add_f32_e32 v0, v8, v9
	v_div_scale_f32 v10, s[16:17], v0, v0, v188
	v_rcp_f32_e32 v11, v10
	v_div_scale_f32 v12, vcc, v188, v0, v188
	v_lshl_add_u64 v[8:9], v[6:7], 0, v[214:215]
	v_fma_f32 v13, -v10, v11, 1.0
	v_fmac_f32_e32 v11, v13, v11
	v_mul_f32_e32 v13, v12, v11
	v_fma_f32 v14, -v10, v13, v12
	v_fmac_f32_e32 v13, v14, v11
	v_fma_f32 v10, -v10, v13, v12
	v_div_fmas_f32 v10, v10, v11, v13
	v_div_fixup_f32 v10, v10, v0, v188
	v_cmp_lt_f32_e32 vcc, 0, v0
	v_lshl_add_u64 v[6:7], v[6:7], 0, v[212:213]
	s_nop 0
	v_cndmask_b32_e32 v0, 0, v10, vcc
	s_waitcnt vmcnt(0)
	v_pk_fma_f32 v[2:3], v[80:81], v[0:1], v[88:89] op_sel_hi:[1,0,1]
	v_pk_fma_f32 v[4:5], v[82:83], v[0:1], v[90:91] op_sel_hi:[1,0,1]
	v_cvt_pk_bf16_f32 v2, v2, v3
	s_nop 0
	v_cvt_pk_bf16_f32 v3, v4, v5
	global_store_dwordx2 v[8:9], v[2:3], off
	s_waitcnt lgkmcnt(0)
	v_pk_fma_f32 v[2:3], v[76:77], v[0:1], v[92:93] op_sel_hi:[1,0,1]
	v_pk_fma_f32 v[4:5], v[78:79], v[0:1], v[94:95] op_sel_hi:[1,0,1]
	v_cvt_pk_bf16_f32 v2, v2, v3
	s_nop 0
	v_cvt_pk_bf16_f32 v3, v4, v5
	global_store_dwordx2 v[8:9], v[2:3], off offset:32
	s_waitcnt lgkmcnt(0)
	v_pk_fma_f32 v[2:3], v[72:73], v[0:1], v[96:97] op_sel_hi:[1,0,1]
	v_pk_fma_f32 v[4:5], v[74:75], v[0:1], v[98:99] op_sel_hi:[1,0,1]
	v_cvt_pk_bf16_f32 v2, v2, v3
	s_nop 0
	v_cvt_pk_bf16_f32 v3, v4, v5
	global_store_dwordx2 v[8:9], v[2:3], off offset:64
	s_waitcnt lgkmcnt(0)
	v_pk_fma_f32 v[2:3], v[84:85], v[0:1], v[100:101] op_sel_hi:[1,0,1]
	v_pk_fma_f32 v[4:5], v[86:87], v[0:1], v[102:103] op_sel_hi:[1,0,1]
	v_cvt_pk_bf16_f32 v2, v2, v3
	ds_bpermute_b32 v0, v217, v238
	v_cvt_pk_bf16_f32 v3, v4, v5
	global_store_dwordx2 v[8:9], v[2:3], off offset:96
	s_waitcnt lgkmcnt(0)
	v_add_f32_e32 v0, v238, v0
	ds_bpermute_b32 v8, v219, v0
	s_waitcnt lgkmcnt(0)
	v_add_f32_e32 v0, v0, v8
	v_div_scale_f32 v8, s[16:17], v0, v0, v184
	v_rcp_f32_e32 v9, v8
	v_div_scale_f32 v10, vcc, v184, v0, v184
	s_mov_b64 s[16:17], 0
	v_fma_f32 v11, -v8, v9, 1.0
	v_fmac_f32_e32 v9, v11, v9
	v_mul_f32_e32 v11, v10, v9
	v_fma_f32 v12, -v8, v11, v10
	v_fmac_f32_e32 v11, v12, v9
	v_fma_f32 v8, -v8, v11, v10
	v_div_fmas_f32 v8, v8, v9, v11
	v_div_fixup_f32 v8, v8, v0, v184
	v_cmp_lt_f32_e32 vcc, 0, v0
	s_nop 1
	v_cndmask_b32_e32 v0, 0, v8, vcc
	v_pk_fma_f32 v[2:3], v[176:177], v[0:1], v[104:105] op_sel_hi:[1,0,1]
	v_pk_fma_f32 v[4:5], v[178:179], v[0:1], v[106:107] op_sel_hi:[1,0,1]
	v_cvt_pk_bf16_f32 v2, v2, v3
	s_nop 0
	v_cvt_pk_bf16_f32 v3, v4, v5
	global_store_dwordx2 v[6:7], v[2:3], off
	s_waitcnt lgkmcnt(0)
	v_pk_fma_f32 v[2:3], v[172:173], v[0:1], v[108:109] op_sel_hi:[1,0,1]
	v_pk_fma_f32 v[4:5], v[174:175], v[0:1], v[110:111] op_sel_hi:[1,0,1]
	v_cvt_pk_bf16_f32 v2, v2, v3
	s_nop 0
	v_cvt_pk_bf16_f32 v3, v4, v5
	global_store_dwordx2 v[6:7], v[2:3], off offset:32
	s_waitcnt lgkmcnt(0)
	v_pk_fma_f32 v[2:3], v[168:169], v[0:1], v[112:113] op_sel_hi:[1,0,1]
	v_pk_fma_f32 v[4:5], v[170:171], v[0:1], v[114:115] op_sel_hi:[1,0,1]
	v_cvt_pk_bf16_f32 v2, v2, v3
	s_nop 0
	v_cvt_pk_bf16_f32 v3, v4, v5
	global_store_dwordx2 v[6:7], v[2:3], off offset:64
	s_waitcnt lgkmcnt(0)
	v_pk_fma_f32 v[2:3], v[180:181], v[0:1], v[116:117] op_sel_hi:[1,0,1]
	v_pk_fma_f32 v[4:5], v[182:183], v[0:1], v[118:119] op_sel_hi:[1,0,1]
	v_cvt_pk_bf16_f32 v2, v2, v3
	s_nop 0
	v_cvt_pk_bf16_f32 v3, v4, v5
	global_store_dwordx2 v[6:7], v[2:3], off offset:96
	s_waitcnt lgkmcnt(0)
	s_barrier

; #define LAS __attribute__((address_space(3)))
; __device__ __forceinline__ int launder_v(int x) { asm volatile("" : "+v"(x)); return x; }
; __device__ __forceinline__ int launder_s(int x) { x = __builtin_amdgcn_readfirstlane(x); asm volatile("" : "+s"(x)); return x; }
; template <int STG, class F>
; __device__ __forceinline__ void stream_tiles(Ctx& C, const TileSrc& src, int tile0, int ntiles, LAS unsigned char* bufs, F&& compute) {
;     if (ntiles <= 0) return;
;     const int nst = (ntiles + STG - 1) / STG, tlast = tile0 + ntiles - 1;
;     v4u rk[STG], rv[STG];
;     { const int tidl = launder_v(C.tid);
; #pragma unroll
;       for (int h = 0; h < STG; ++h) { const int t = tile0 + h; tile_fetch(src, 64 * (t < tlast ? t : tlast), tidl, rk[h], rv[h]); }
; #pragma unroll
;       for (int h = 0; h < STG; ++h) tile_store(bufs + h * 16384, tidl, rk[h], rv[h]); }
;     __syncthreads();
; __device__ __forceinline__ void nsa_block_task(Ctx& C, int task, bf16* ONSA_OUT) {
;     ...
; #pragma unroll
;         for (int cg = 0; cg < 2; ++cg)
; #pragma unroll
;             for (int c = 0; c < 4; ++c) oc[cg][c] = o[cg][c] * g_c[cg];
;     ...
;     f4* STASH = WSP(f4, WS_STASH) + (size_t)(C.bid * NWAVES + w) * 512;
; #pragma unroll
;     for (int cg = 0; cg < 2; ++cg)
; #pragma unroll
;         for (int c = 0; c < 4; ++c) STASH[(cg * 4 + c) * 64 + lane] = oc[cg][c];
;     __syncthreads();
;     {
;         AttnAcc a[2]; attn_init(a[0]); attn_init(a[1]);
;         const int kvs = launder_s(kvh);
;         const TileSrc src{WSP(bf16, WS_KS) + (size_t)kvs * RP * 64, WSP(bf16, WS_VST) + (size_t)kvs * 64 * RP, RP};
;         int cw = -1; unsigned aw0 = 0u, aw1 = 0u;
;         stream_tiles<4>(C, src, 0, qb, bufs, [&](const LAS unsigned char* buf, int j) {
.LBB0_1206:
	s_or_b64 exec, exec, s[16:17]
	v_pk_mul_f32 v[32:33], v[186:187], v[32:33] op_sel_hi:[0,1]
	v_pk_mul_f32 v[34:35], v[186:187], v[34:35] op_sel_hi:[0,1]
	s_mov_b32 s3, s97
	v_pk_mul_f32 v[48:49], v[186:187], v[48:49] op_sel_hi:[0,1]
	v_pk_mul_f32 v[50:51], v[186:187], v[50:51] op_sel_hi:[0,1]
	v_pk_mul_f32 v[44:45], v[186:187], v[44:45] op_sel_hi:[0,1]
	v_pk_mul_f32 v[46:47], v[186:187], v[46:47] op_sel_hi:[0,1]
	v_pk_mul_f32 v[36:37], v[182:183], v[36:37] op_sel_hi:[0,1]
	v_pk_mul_f32 v[38:39], v[182:183], v[38:39] op_sel_hi:[0,1]
	v_pk_mul_f32 v[40:41], v[182:183], v[40:41] op_sel_hi:[0,1]
	v_pk_mul_f32 v[42:43], v[182:183], v[42:43] op_sel_hi:[0,1]
	v_pk_mul_f32 v[28:29], v[186:187], v[28:29] op_sel_hi:[0,1]
	v_pk_mul_f32 v[30:31], v[186:187], v[30:31] op_sel_hi:[0,1]
	v_pk_mul_f32 v[20:21], v[182:183], v[20:21] op_sel_hi:[0,1]
	v_pk_mul_f32 v[22:23], v[182:183], v[22:23] op_sel_hi:[0,1]
	v_pk_mul_f32 v[24:25], v[182:183], v[24:25] op_sel_hi:[0,1]
	v_pk_mul_f32 v[26:27], v[182:183], v[26:27] op_sel_hi:[0,1]
	s_waitcnt lgkmcnt(0)
	global_store_dwordx4 v[200:201], v[32:35], off
	global_store_dwordx4 v[200:201], v[48:51], off offset:1024
	global_store_dwordx4 v[200:201], v[28:31], off offset:2048
	global_store_dwordx4 v[200:201], v[44:47], off offset:3072
	global_store_dwordx4 v[202:203], v[20:23], off
	global_store_dwordx4 v[202:203], v[36:39], off offset:1024
	global_store_dwordx4 v[202:203], v[24:27], off offset:2048
	global_store_dwordx4 v[202:203], v[40:43], off offset:3072
	s_waitcnt lgkmcnt(0)
	s_barrier
	s_mul_hi_i32 s17, s3, 0x208000
	s_mul_i32 s3, s3, 0x208000
	s_add_u32 s18, s79, s3
	s_addc_u32 s19, s80, s17
	s_add_u32 s16, s81, s3
	s_addc_u32 s17, s82, s17
	s_cmp_eq_u32 s94, 0
	s_mov_b32 s26, 0
	s_cbranch_scc1 .LBB0_1229
	v_mov_b32_e32 v36, v189
	s_add_i32 s3, s94, 3
	v_ashrrev_i32_e32 v20, 3, v36
	v_lshlrev_b32_e32 v28, 4, v36
	v_and_b32_e32 v0, 0x70, v28
	v_ashrrev_i32_e32 v21, 31, v20
	v_mov_b64_e32 v[22:23], s[16:17]
	v_lshl_add_u64 v[2:3], s[18:19], 0, v[0:1]
	v_mad_i64_i32 v[22:23], s[20:21], v20, s92, v[22:23]
	v_lshlrev_b64 v[24:25], 7, v[20:21]
	s_cmp_eq_u32 s0, 0
	v_lshl_add_u64 v[24:25], v[2:3], 0, v[24:25]
	s_cselect_b32 s20, 0, 64
	v_lshl_add_u64 v[22:23], v[22:23], 0, v[0:1]
	global_load_dwordx4 v[56:59], v[24:25], off
	global_load_dwordx4 v[60:63], v[22:23], off
	v_add_u32_e32 v24, s20, v20
	v_ashrrev_i32_e32 v25, 31, v24
	v_lshlrev_b64 v[24:25], 7, v[24:25]
	v_lshl_add_u64 v[24:25], v[2:3], 0, v[24:25]
	s_lshl_b32 s50, s20, 1
	s_min_u32 s20, s0, 2
	v_lshl_add_u64 v[26:27], v[22:23], 0, s[50:51]
	global_load_dwordx4 v[64:67], v[24:25], off
	global_load_dwordx4 v[68:71], v[26:27], off
	v_lshl_add_u32 v24, s20, 6, v20
	v_ashrrev_i32_e32 v25, 31, v24
	v_lshlrev_b64 v[24:25], 7, v[24:25]
	v_lshl_add_u64 v[24:25], v[2:3], 0, v[24:25]
	s_lshl_b32 s50, s20, 7
	s_min_u32 s20, s0, 3
	v_lshl_add_u64 v[26:27], v[22:23], 0, s[50:51]
	global_load_dwordx4 v[72:75], v[24:25], off
	global_load_dwordx4 v[76:79], v[26:27], off
	v_lshl_add_u32 v24, s20, 6, v20
	v_ashrrev_i32_e32 v25, 31, v24
	v_lshlrev_b64 v[24:25], 7, v[24:25]
	v_lshl_add_u64 v[2:3], v[2:3], 0, v[24:25]
	s_lshl_b32 s50, s20, 7
	v_lshl_add_u64 v[22:23], v[22:23], 0, s[50:51]
	global_load_dwordx4 v[80:83], v[2:3], off
	global_load_dwordx4 v[84:87], v[22:23], off
	v_mul_lo_u32 v198, v20, s92
	v_lshl_add_u32 v185, v20, 7, v0
	v_add_u32_e32 v198, v198, v0
	s_add_i32 s24, s94, 3
	s_lshr_b32 s24, s24, 2
	s_cmp_lt_u32 s24, 2
	s_cbranch_scc1 .Lseld_pro1
	s_mov_b32 s28, 4
	s_min_i32 s24, s28, s0
	s_lshl_b32 s98, s24, 13
	s_add_u32 s98, s18, s98
	s_addc_u32 s99, s19, 0
	global_load_dwordx4 v[174:177], v185, s[98:99]
	s_lshl_b32 s100, s24, 7
	s_add_u32 s100, s16, s100
	s_addc_u32 s101, s17, 0
	global_load_dwordx4 v[178:181], v198, s[100:101]
	s_add_i32 s24, s28, 1
	s_min_i32 s24, s24, s0
	s_lshl_b32 s98, s24, 13
	s_add_u32 s98, s18, s98
	s_addc_u32 s99, s19, 0
	global_load_dwordx4 v[204:207], v185, s[98:99]
	s_lshl_b32 s100, s24, 7
	s_add_u32 s100, s16, s100
	s_addc_u32 s101, s17, 0
	global_load_dwordx4 v[234:237], v198, s[100:101]
	s_add_i32 s24, s28, 2
	s_min_i32 s24, s24, s0
	s_lshl_b32 s98, s24, 13
	s_add_u32 s98, s18, s98
	s_addc_u32 s99, s19, 0
	global_load_dwordx4 v[238:241], v185, s[98:99]
	s_lshl_b32 s100, s24, 7
	s_add_u32 s100, s16, s100
	s_addc_u32 s101, s17, 0
	global_load_dwordx4 v[242:245], v198, s[100:101]
	s_add_i32 s24, s28, 3
	s_min_i32 s24, s24, s0
	s_lshl_b32 s98, s24, 13
	s_add_u32 s98, s18, s98
	s_addc_u32 s99, s19, 0
	global_load_dwordx4 v[246:249], v185, s[98:99]
	s_lshl_b32 s100, s24, 7
	s_add_u32 s100, s16, s100
	s_addc_u32 s101, s17, 0
	global_load_dwordx4 v[250:253], v198, s[100:101]
.Lseld_pro1:
	v_lshlrev_b32_e32 v0, 2, v20
	v_lshrrev_b32_e32 v21, 1, v20
	v_mov_b32_e32 v2, v1
	v_mov_b32_e32 v3, v1
	v_and_b32_e32 v22, 35, v20
	v_lshlrev_b32_e32 v20, 7, v20
	v_bitop3_b32 v23, v28, s91, v36 bitop3:0x48
	v_and_b32_e32 v24, 16, v0
	v_and_b32_e32 v21, 12, v21
	v_add3_u32 v37, 0, v20, v23
	v_mov_b32_e32 v0, v1
	v_or3_b32 v38, v24, v22, v21
	v_mov_b64_e32 v[22:23], v[2:3]
	v_mov_b64_e32 v[26:27], v[2:3]
	v_mov_b64_e32 v[30:31], v[2:3]
	v_mov_b64_e32 v[34:35], v[2:3]
	v_mov_b64_e32 v[42:43], v[2:3]
	v_mov_b64_e32 v[46:47], v[2:3]
	v_mov_b64_e32 v[50:51], v[2:3]
	v_mov_b64_e32 v[54:55], v[2:3]
	v_mov_b64_e32 v[20:21], v[0:1]
	v_mov_b64_e32 v[24:25], v[0:1]
	v_mov_b64_e32 v[28:29], v[0:1]
	v_mov_b64_e32 v[32:33], v[0:1]
	v_mov_b64_e32 v[40:41], v[0:1]
	v_mov_b64_e32 v[44:45], v[0:1]
	v_mov_b64_e32 v[48:49], v[0:1]
	v_mov_b64_e32 v[52:53], v[0:1]
	v_lshrrev_b32_e32 v2, 1, v38
	v_xor_b32_e32 v2, v2, v36
	v_lshlrev_b32_e32 v2, 4, v2
	v_lshlrev_b32_e32 v0, 7, v38
	v_and_b32_e32 v2, 0x70, v2
	s_mov_b32 s27, 0
	v_mov_b32_e32 v169, 0xc4800000
	v_mov_b32_e32 v168, 0
	s_mov_b32 s22, -1
	s_mov_b32 s28, 0
	s_mov_b32 s31, 0
	s_mov_b32 s30, 0
	s_lshr_b32 s29, s3, 2
	v_add3_u32 v0, 0, v0, v2
	v_mov_b32_e32 v36, 0
	v_mov_b32_e32 v170, 0xc4800000
	s_mov_b32 s23, 0
	v_ashrrev_i32_e32 v226, 4, v190
	v_lshrrev_b32_e32 v225, 1, v190
	v_bitop3_b32 v233, v225, v226, 7 bitop3:0x6c
	v_lshlrev_b32_e32 v254, 7, v190
	v_add_u32_e32 v226, 4, v226
	v_lshlrev_b32_e32 v233, 4, v233
	v_and_b32_e32 v254, 0x780, v254
	v_bitop3_b32 v226, v226, v225, 7 bitop3:0x78
	v_lshlrev_b32_e32 v226, 4, v226
	v_add_u32_e32 v225, v254, v233
	v_add_u32_e32 v226, v254, v226
	s_cmp_lt_u32 s29, 2
	s_cbranch_scc1 .Lseld_pro2
	s_waitcnt vmcnt(8) lgkmcnt(0)
	s_branch .Lseld_pro3

; __device__ __forceinline__ int launder_v(int x) { asm volatile("" : "+v"(x)); return x; }
; template <int STG, class F>
; __device__ __forceinline__ void stream_tiles(Ctx& C, const TileSrc& src, int tile0, int ntiles, LAS unsigned char* bufs, F&& compute) {
;     ...
;       for (int h = 0; h < STG; ++h) tile_store(bufs + h * 16384, tidl, rk[h], rv[h]); }
;     __syncthreads();
; #pragma unroll 1
;     for (int st = 0; st < nst; ++st) {
;         const int tidl = launder_v(C.tid);
;         const bool more = st + 1 < nst;
;         if (more) {
; #pragma unroll
;             for (int h = 0; h < STG; ++h) { const int t = tile0 + STG * (st + 1) + h; tile_fetch(src, 64 * (t < tlast ? t : tlast), tidl, rk[h], rv[h]); } }
.Lseld_pro3:
	ds_write_b128 v0, v[56:59]
	ds_write_b128 v37, v[60:63] offset:8192
	ds_write_b128 v0, v[64:67] offset:16384
	ds_write_b128 v37, v[68:71] offset:24576
	ds_write_b128 v0, v[72:75] offset:32768
	ds_write_b128 v37, v[76:79] offset:40960
	ds_write_b128 v0, v[80:83] offset:49152
	ds_write_b128 v37, v[84:87] offset:57344
	s_waitcnt lgkmcnt(0)
	s_barrier
.LBB0_1208:
	s_add_i32 s34, s23, 1
	v_mov_b32_e32 v37, v189
	s_cmp_lt_u32 s34, s29
	s_cselect_b64 s[20:21], -1, 0
	v_ashrrev_i32_e32 v38, 3, v37
	v_lshlrev_b32_e32 v39, 4, v37
	s_add_i32 s3, s34, 1
	s_cmp_ge_u32 s3, s29
	s_cbranch_scc1 .LBB0_1210
	s_lshl_b32 s3, s3, 2
	s_bitcmp1_b32 s34, 0
	s_cbranch_scc0 .Lseld_ldB
	s_min_i32 s24, s3, s0
	s_lshl_b32 s98, s24, 13
	s_add_u32 s98, s18, s98
	s_addc_u32 s99, s19, 0
	global_load_dwordx4 v[56:59], v185, s[98:99]
	s_lshl_b32 s100, s24, 7
	s_add_u32 s100, s16, s100
	s_addc_u32 s101, s17, 0
	global_load_dwordx4 v[60:63], v198, s[100:101]
	s_add_i32 s24, s3, 1
	s_min_i32 s24, s24, s0
	s_lshl_b32 s98, s24, 13
	s_add_u32 s98, s18, s98
	s_addc_u32 s99, s19, 0
	global_load_dwordx4 v[64:67], v185, s[98:99]
	s_lshl_b32 s100, s24, 7
	s_add_u32 s100, s16, s100
	s_addc_u32 s101, s17, 0
	global_load_dwordx4 v[68:71], v198, s[100:101]
	s_add_i32 s24, s3, 2
	s_min_i32 s24, s24, s0
	s_lshl_b32 s98, s24, 13
	s_add_u32 s98, s18, s98
	s_addc_u32 s99, s19, 0
	global_load_dwordx4 v[72:75], v185, s[98:99]
	s_lshl_b32 s100, s24, 7
	s_add_u32 s100, s16, s100
	s_addc_u32 s101, s17, 0
	global_load_dwordx4 v[76:79], v198, s[100:101]
	s_add_i32 s24, s3, 3
	s_min_i32 s24, s24, s0
	s_lshl_b32 s98, s24, 13
	s_add_u32 s98, s18, s98
	s_addc_u32 s99, s19, 0
	global_load_dwordx4 v[80:83], v185, s[98:99]
	s_lshl_b32 s100, s24, 7
	s_add_u32 s100, s16, s100
	s_addc_u32 s101, s17, 0
	global_load_dwordx4 v[84:87], v198, s[100:101]
	s_branch .LBB0_1210
.Lseld_ldB:
	s_min_i32 s24, s3, s0
	s_lshl_b32 s98, s24, 13
	s_add_u32 s98, s18, s98
	s_addc_u32 s99, s19, 0
	global_load_dwordx4 v[174:177], v185, s[98:99]
	s_lshl_b32 s100, s24, 7
	s_add_u32 s100, s16, s100
	s_addc_u32 s101, s17, 0
	global_load_dwordx4 v[178:181], v198, s[100:101]
	s_add_i32 s24, s3, 1
	s_min_i32 s24, s24, s0
	s_lshl_b32 s98, s24, 13
	s_add_u32 s98, s18, s98
	s_addc_u32 s99, s19, 0
	global_load_dwordx4 v[204:207], v185, s[98:99]
	s_lshl_b32 s100, s24, 7
	s_add_u32 s100, s16, s100
	s_addc_u32 s101, s17, 0
	global_load_dwordx4 v[234:237], v198, s[100:101]
	s_add_i32 s24, s3, 2
	s_min_i32 s24, s24, s0
	s_lshl_b32 s98, s24, 13
	s_add_u32 s98, s18, s98
	s_addc_u32 s99, s19, 0
	global_load_dwordx4 v[238:241], v185, s[98:99]
	s_lshl_b32 s100, s24, 7
	s_add_u32 s100, s16, s100
	s_addc_u32 s101, s17, 0
	global_load_dwordx4 v[242:245], v198, s[100:101]
	s_add_i32 s24, s3, 3
	s_min_i32 s24, s24, s0
	s_lshl_b32 s98, s24, 13
	s_add_u32 s98, s18, s98
	s_addc_u32 s99, s19, 0
	global_load_dwordx4 v[246:249], v185, s[98:99]
	s_lshl_b32 s100, s24, 7
	s_add_u32 s100, s16, s100
	s_addc_u32 s101, s17, 0
	global_load_dwordx4 v[250:253], v198, s[100:101]

; __device__ __forceinline__ bf16x8 pack8(const f4& a, const f4& b) { return __builtin_bit_cast(bf16x8, pack8u(a, b)); }
; __device__ __forceinline__ float fexp2(float x) { return __builtin_amdgcn_exp2f(x); }
; #define MFMA16(a, b, c) __builtin_amdgcn_mfma_f32_16x16x32_bf16((a), (b), (c), 0, 0, 0)
;     ...
;     float ps = 0.f; bf16x8 pb[2];
; #pragma unroll
;     for (int ch = 0; ch < 2; ++ch) { f4 p0, p1;
; #pragma unroll
;         for (int j = 0; j < 4; ++j) { p0[j] = fexp2(s[ch][0][j] - a.m); p1[j] = fexp2(s[ch][1][j] - a.m); ps += p0[j] + p1[j]; }
;         pb[ch] = pack8(p0, p1); }
;     a.l += ps;
; #pragma unroll
;     for (int ch = 0; ch < 2; ++ch)
; #pragma unroll
;         for (int c = 0; c < 4; ++c) a.o[c] = MFMA16(vf[ch][c], pb[ch], a.o[c]);
.LBB0_1211:
	v_exp_f32_e32 v140, v140
	v_exp_f32_e32 v141, v141
	v_exp_f32_e32 v142, v142
	v_exp_f32_e32 v143, v143
	v_exp_f32_e32 v144, v144
	v_exp_f32_e32 v145, v145
	v_pk_add_f32 v[2:3], v[140:141], v[142:143]
	v_exp_f32_e32 v146, v146
	v_exp_f32_e32 v147, v147
	v_cvt_pk_bf16_f32 v140, v140, v141
	v_cvt_pk_bf16_f32 v141, v142, v143
	v_pk_add_f32 v[2:3], v[2:3], v[144:145]
	v_cvt_pk_bf16_f32 v142, v144, v145
	v_pk_add_f32 v[2:3], v[2:3], v[146:147]
	v_cvt_pk_bf16_f32 v143, v146, v147
	v_exp_f32_e32 v128, v128
	v_exp_f32_e32 v129, v129
	s_waitcnt lgkmcnt(4)
	v_mfma_f32_16x16x32_bf16 v[32:35], v[116:119], v[140:143], v[32:35]
	v_exp_f32_e32 v130, v130
	v_exp_f32_e32 v131, v131
	v_mfma_f32_16x16x32_bf16 v[28:31], v[112:115], v[140:143], v[28:31]
	v_exp_f32_e32 v120, v120
	v_exp_f32_e32 v121, v121
	v_pk_add_f32 v[2:3], v[2:3], v[128:129]
	v_mfma_f32_16x16x32_bf16 v[24:27], v[108:111], v[140:143], v[24:27]
	v_exp_f32_e32 v122, v122
	v_exp_f32_e32 v123, v123
	v_pk_add_f32 v[2:3], v[2:3], v[130:131]
	v_mfma_f32_16x16x32_bf16 v[20:23], v[104:107], v[140:143], v[20:23]
	v_cvt_pk_bf16_f32 v128, v128, v129
	v_cvt_pk_bf16_f32 v129, v130, v131
	v_pk_add_f32 v[2:3], v[2:3], v[120:121]
	v_cvt_pk_bf16_f32 v130, v120, v121
	v_pk_add_f32 v[2:3], v[2:3], v[122:123]
	v_cvt_pk_bf16_f32 v131, v122, v123
	v_add_f32_e32 v0, v2, v3
	v_add_f32_e32 v168, v168, v0
	s_waitcnt lgkmcnt(0)
	v_mfma_f32_16x16x32_bf16 v[32:35], v[96:99], v[128:131], v[32:35]
	v_mfma_f32_16x16x32_bf16 v[28:31], v[100:103], v[128:131], v[28:31]
	v_mfma_f32_16x16x32_bf16 v[24:27], v[92:95], v[128:131], v[24:27]
	v_mfma_f32_16x16x32_bf16 v[20:23], v[88:91], v[128:131], v[20:23]

; __device__ __forceinline__ float fexp2(float x) { return __builtin_amdgcn_exp2f(x); }
; __device__ __forceinline__ int launder_v(int x) { asm volatile("" : "+v"(x)); return x; }
; #define MFMA16(a, b, c) __builtin_amdgcn_mfma_f32_16x16x32_bf16((a), (b), (c), 0, 0, 0)
;     f4 s[2][2];
; #pragma unroll
;     for (int ch = 0; ch < 2; ++ch)
; #pragma unroll
;         for (int kt = 0; kt < 2; ++kt) { f4 t = (f4){colbias, colbias, colbias, colbias}; t = MFMA16(kf[ch][kt][0], bq[0], t); s[ch][kt] = MFMA16(kf[ch][kt][1], bq[1], t); }
;     float mx = -1e30f;
; #pragma unroll
;     for (int ch = 0; ch < 2; ++ch)
; #pragma unroll
;         for (int h = 0; h < 2; ++h) mx = fmaxf(mx, fmaxf(fmaxf(s[ch][h][0], s[ch][h][1]), fmaxf(s[ch][h][2], s[ch][h][3])));
;     if (__any(mx > a.m + MAX_SLACK)) {
;         mx = fmaxf(mx, __shfl_xor(mx, 16)); mx = fmaxf(mx, __shfl_xor(mx, 32));
;         const float mn = fmaxf(a.m, mx), alpha = fexp2(a.m - mn); a.m = mn; a.l *= alpha;
; #pragma unroll
;         for (int c = 0; c < 4; ++c) a.o[c] = a.o[c] * alpha;
;     }
; __device__ __forceinline__ void nsa_block_task(Ctx& C, int task, bf16* ONSA_OUT) {
;     ...
;             if ((j >> 5) != cw) { cw = j >> 5; aw0 = (unsigned)__builtin_amdgcn_readfirstlane((int)ANYM[cw]); aw1 = (unsigned)__builtin_amdgcn_readfirstlane((int)ANYM[8 + cw]); }
;             bool any[2]; any[0] = (aw0 >> (j & 31)) & 1u; any[1] = (aw1 >> (j & 31)) & 1u;
;             if (any[0] || any[1]) {
;                 bool mysel[2];
; #pragma unroll
;                 for (int cg = 0; cg < 2; ++cg) mysel[cg] = (SELM[(4 * cg + qi) * 8 + (j >> 5)] >> (j & 31)) & 1u;
;                 bf16x8 kf[2][2][2], vf[2][4]; { const int ll = launder_v(lane);
; #pragma unroll
;                     for (int ch = 0; ch < 2; ++ch) { tile_read_k(buf, ch, ll, kf[ch]); tile_read_v(buf, ch, ll, vf[ch]); } }
; #pragma unroll
;                 for (int cg = 0; cg < 2; ++cg) if (any[cg]) attn_tile64_full(a[cg], kf, vf, bq[cg], mysel[cg] ? 0.f : -3e30f);
.LBB0_1217:
	s_add_i32 s40, s35, s39
	s_lshl_b32 s3, 1, s40
	s_and_b32 s22, s30, s3
	s_and_b32 s3, s31, s3
	s_or_b32 s41, s22, s3
	s_cmp_lg_u32 s22, 0
	s_cselect_b64 s[24:25], -1, 0
	s_cmp_lg_u32 s3, 0
	s_cselect_b64 s[22:23], -1, 0
	s_cmp_lg_u32 s41, 0
	s_cselect_b64 s[42:43], -1, 0
	s_andn2_b64 vcc, exec, s[42:43]
	s_cbranch_vccnz .LBB0_1212
	s_waitcnt lgkmcnt(0)
	ds_read2_b32 v[2:3], v171 offset1:32
	s_andn2_b64 vcc, exec, s[24:25]
	v_add_u32_e32 v89, s36, v225
	v_add_u32_e32 v0, s36, v226
	ds_read_b128 v[140:143], v89
	ds_read_b128 v[144:147], v89 offset:2048
	ds_read_b128 v[148:151], v0
	ds_read_b128 v[128:131], v0 offset:2048
	ds_read_b128 v[136:139], v89 offset:4096
	ds_read_b128 v[124:127], v89 offset:6144
	ds_read_b128 v[132:135], v0 offset:4096
	ds_read_b128 v[120:123], v0 offset:6144
	ds_read_b128 v[116:119], v89 offset:8192
	ds_read_b128 v[112:115], v89 offset:10240
	ds_read_b128 v[108:111], v89 offset:12288
	ds_read_b128 v[104:107], v89 offset:14336
	ds_read_b128 v[96:99], v0 offset:8192
	ds_read_b128 v[100:103], v0 offset:10240
	ds_read_b128 v[92:95], v0 offset:12288
	ds_read_b128 v[88:91], v0 offset:14336
	s_cbranch_vccnz .LBB0_1222
	s_waitcnt lgkmcnt(12)
	v_bfe_i32 v0, v2, s40, 1
	v_bfi_b32 v156, v0, 0, v231
	v_sub_f32_e32 v156, v156, v170
	v_mov_b32_e32 v157, v156
	v_mov_b32_e32 v158, v156
	v_mov_b32_e32 v159, v156
	s_nop 1
	v_mfma_f32_16x16x32_bf16 v[152:155], v[140:143], v[4:7], v[156:159]
	v_mfma_f32_16x16x32_bf16 v[160:163], v[148:151], v[8:11], v[152:155]
	v_mfma_f32_16x16x32_bf16 v[152:155], v[144:147], v[4:7], v[156:159]
	v_mfma_f32_16x16x32_bf16 v[164:167], v[128:131], v[8:11], v[152:155]
	s_nop 5
	v_max3_f32 v0, v160, v161, v162
	v_max3_f32 v0, v0, v163, s93
	s_waitcnt lgkmcnt(8)
	v_mfma_f32_16x16x32_bf16 v[152:155], v[136:139], v[4:7], v[156:159]
	v_max3_f32 v0, v0, v164, v165
	v_max3_f32 v0, v0, v166, v167
	v_mfma_f32_16x16x32_bf16 v[156:159], v[124:127], v[4:7], v[156:159]
	v_mfma_f32_16x16x32_bf16 v[152:155], v[132:135], v[8:11], v[152:155]
	v_mfma_f32_16x16x32_bf16 v[156:159], v[120:123], v[8:11], v[156:159]
	s_nop 6
	v_max3_f32 v0, v0, v152, v153
	v_max3_f32 v0, v0, v154, v155
	v_max3_f32 v0, v0, v156, v157
	v_max3_f32 v0, v0, v158, v159
	v_cmp_lt_f32_e32 vcc, 0x41000000, v0
	s_cbranch_vccz .LBB0_1221
	ds_bpermute_b32 v2, v217, v0
	v_max_f32_e32 v0, v0, v0
	s_waitcnt lgkmcnt(0)
	v_max_f32_e32 v2, v2, v2
	v_max_f32_e32 v0, v0, v2
	ds_bpermute_b32 v2, v219, v0
	s_waitcnt lgkmcnt(0)
	v_max3_f32 v2, 0, v0, v2
	v_sub_f32_e32 v0, 0, v2
	v_exp_f32_e32 v0, v0
	v_add_f32_e32 v170, v170, v2
	v_sub_f32_e32 v160, v160, v2
	v_sub_f32_e32 v161, v161, v2
	v_sub_f32_e32 v162, v162, v2
	v_sub_f32_e32 v163, v163, v2
	v_sub_f32_e32 v164, v164, v2
	v_sub_f32_e32 v165, v165, v2
	v_sub_f32_e32 v166, v166, v2
	v_sub_f32_e32 v167, v167, v2
	v_sub_f32_e32 v152, v152, v2
	v_sub_f32_e32 v153, v153, v2
	v_sub_f32_e32 v154, v154, v2
	v_sub_f32_e32 v155, v155, v2
	v_sub_f32_e32 v156, v156, v2
	v_sub_f32_e32 v157, v157, v2
	v_sub_f32_e32 v158, v158, v2
	v_sub_f32_e32 v159, v159, v2
	v_mul_f32_e32 v36, v36, v0
	v_pk_mul_f32 v[54:55], v[54:55], v[0:1] op_sel_hi:[1,0]
	v_pk_mul_f32 v[52:53], v[52:53], v[0:1] op_sel_hi:[1,0]
	v_pk_mul_f32 v[50:51], v[50:51], v[0:1] op_sel_hi:[1,0]
	v_pk_mul_f32 v[48:49], v[48:49], v[0:1] op_sel_hi:[1,0]
	v_pk_mul_f32 v[46:47], v[46:47], v[0:1] op_sel_hi:[1,0]
	v_pk_mul_f32 v[44:45], v[44:45], v[0:1] op_sel_hi:[1,0]
	v_pk_mul_f32 v[42:43], v[42:43], v[0:1] op_sel_hi:[1,0]
	v_pk_mul_f32 v[40:41], v[40:41], v[0:1] op_sel_hi:[1,0]
.LBB0_1221:
	v_exp_f32_e32 v160, v160
	v_exp_f32_e32 v161, v161
	v_exp_f32_e32 v162, v162
	v_exp_f32_e32 v163, v163
	v_exp_f32_e32 v164, v164
	v_exp_f32_e32 v165, v165
	v_pk_add_f32 v[172:173], v[160:161], v[162:163]
	v_exp_f32_e32 v166, v166
	v_exp_f32_e32 v167, v167
	v_cvt_pk_bf16_f32 v160, v160, v161
	v_cvt_pk_bf16_f32 v161, v162, v163
	v_pk_add_f32 v[172:173], v[172:173], v[164:165]
	v_cvt_pk_bf16_f32 v162, v164, v165
	v_pk_add_f32 v[172:173], v[172:173], v[166:167]
	v_cvt_pk_bf16_f32 v163, v166, v167
	v_exp_f32_e32 v152, v152
	v_exp_f32_e32 v153, v153
	s_waitcnt lgkmcnt(4)
	v_mfma_f32_16x16x32_bf16 v[52:55], v[116:119], v[160:163], v[52:55]
	v_exp_f32_e32 v154, v154
	v_exp_f32_e32 v155, v155
	v_mfma_f32_16x16x32_bf16 v[48:51], v[112:115], v[160:163], v[48:51]
	v_exp_f32_e32 v156, v156
	v_exp_f32_e32 v157, v157
	v_pk_add_f32 v[172:173], v[172:173], v[152:153]
	v_mfma_f32_16x16x32_bf16 v[44:47], v[108:111], v[160:163], v[44:47]
	v_exp_f32_e32 v158, v158
	v_exp_f32_e32 v159, v159
	v_pk_add_f32 v[172:173], v[172:173], v[154:155]
	v_mfma_f32_16x16x32_bf16 v[40:43], v[104:107], v[160:163], v[40:43]
	v_cvt_pk_bf16_f32 v152, v152, v153
	v_cvt_pk_bf16_f32 v153, v154, v155
	v_pk_add_f32 v[172:173], v[172:173], v[156:157]
	v_cvt_pk_bf16_f32 v154, v156, v157
	v_pk_add_f32 v[172:173], v[172:173], v[158:159]
	v_cvt_pk_bf16_f32 v155, v158, v159
	v_add_f32_e32 v0, v172, v173
	v_add_f32_e32 v36, v36, v0
	s_waitcnt lgkmcnt(0)
	v_mfma_f32_16x16x32_bf16 v[52:55], v[96:99], v[152:155], v[52:55]
	v_mfma_f32_16x16x32_bf16 v[48:51], v[100:103], v[152:155], v[48:51]
	v_mfma_f32_16x16x32_bf16 v[44:47], v[92:95], v[152:155], v[44:47]
	v_mfma_f32_16x16x32_bf16 v[40:43], v[88:91], v[152:155], v[40:43]
; __device__ __forceinline__ int launder_v(int x) { asm volatile("" : "+v"(x)); return x; }
; template <int STG, class F>
; __device__ __forceinline__ void stream_tiles(Ctx& C, const TileSrc& src, int tile0, int ntiles, LAS unsigned char* bufs, F&& compute) {
;     ...
;         if (more) {
; #pragma unroll
;             for (int h = 0; h < STG; ++h) tile_store(bufs + ((st + 1) & 1) * (STG * 16384) + h * 16384, tidl, rk[h], rv[h]); }
;         __syncthreads();
; __device__ __forceinline__ void nsa_block_task(Ctx& C, int task, bf16* ONSA_OUT) {
;     ...
;                 for (int cg = 0; cg < 2; ++cg) mysel[cg] = (SELM[(4 * cg + qi) * 8 + (j >> 5)] >> (j & 31)) & 1u;
;                 bf16x8 kf[2][2][2], vf[2][4]; { const int ll = launder_v(lane);
; #pragma unroll
;                     for (int ch = 0; ch < 2; ++ch) { tile_read_k(buf, ch, ll, kf[ch]); tile_read_v(buf, ch, ll, vf[ch]); } }
; #pragma unroll
;                 for (int cg = 0; cg < 2; ++cg) if (any[cg]) attn_tile64_full(a[cg], kf, vf, bq[cg], mysel[cg] ? 0.f : -3e30f);
.LBB0_1222:
	s_andn2_b64 vcc, exec, s[22:23]
	s_cbranch_vccnz .LBB0_1212
	s_waitcnt lgkmcnt(12)
	v_bfe_i32 v0, v3, s40, 1
	v_bfi_b32 v152, v0, 0, v231
	v_sub_f32_e32 v152, v152, v169
	v_mov_b32_e32 v153, v152
	v_mov_b32_e32 v154, v152
	v_mov_b32_e32 v155, v152
	s_nop 1
	v_mfma_f32_16x16x32_bf16 v[140:143], v[140:143], v[12:15], v[152:155]
	v_mfma_f32_16x16x32_bf16 v[144:147], v[144:147], v[12:15], v[152:155]
	v_mfma_f32_16x16x32_bf16 v[140:143], v[148:151], v[16:19], v[140:143]
	v_mfma_f32_16x16x32_bf16 v[144:147], v[128:131], v[16:19], v[144:147]
	s_waitcnt lgkmcnt(8)
	v_mfma_f32_16x16x32_bf16 v[128:131], v[136:139], v[12:15], v[152:155]
	s_nop 5
	v_max3_f32 v0, v140, v141, v142
	v_max3_f32 v0, v0, v143, s93
	v_mfma_f32_16x16x32_bf16 v[124:127], v[124:127], v[12:15], v[152:155]
	v_max3_f32 v0, v0, v144, v145
	v_mfma_f32_16x16x32_bf16 v[128:131], v[132:135], v[16:19], v[128:131]
	v_max3_f32 v0, v0, v146, v147
	v_mfma_f32_16x16x32_bf16 v[120:123], v[120:123], v[16:19], v[124:127]
	s_nop 5
	v_max3_f32 v0, v0, v128, v129
	v_max3_f32 v0, v0, v130, v131
	v_max3_f32 v0, v0, v120, v121
	v_max3_f32 v0, v0, v122, v123
	v_cmp_lt_f32_e32 vcc, 0x41000000, v0
	s_cbranch_vccz .LBB0_1211
	ds_bpermute_b32 v2, v217, v0
	v_max_f32_e32 v0, v0, v0
	s_waitcnt lgkmcnt(0)
	v_max_f32_e32 v2, v2, v2
	v_max_f32_e32 v0, v0, v2
	ds_bpermute_b32 v2, v219, v0
	s_waitcnt lgkmcnt(0)
	v_max3_f32 v2, 0, v0, v2
	v_sub_f32_e32 v0, 0, v2
	v_exp_f32_e32 v0, v0
	v_add_f32_e32 v169, v169, v2
	v_sub_f32_e32 v140, v140, v2
	v_sub_f32_e32 v141, v141, v2
	v_sub_f32_e32 v142, v142, v2
	v_sub_f32_e32 v143, v143, v2
	v_sub_f32_e32 v144, v144, v2
	v_sub_f32_e32 v145, v145, v2
	v_sub_f32_e32 v146, v146, v2
	v_sub_f32_e32 v147, v147, v2
	v_sub_f32_e32 v128, v128, v2
	v_sub_f32_e32 v129, v129, v2
	v_sub_f32_e32 v130, v130, v2
	v_sub_f32_e32 v131, v131, v2
	v_sub_f32_e32 v120, v120, v2
	v_sub_f32_e32 v121, v121, v2
	v_sub_f32_e32 v122, v122, v2
	v_sub_f32_e32 v123, v123, v2
	v_mul_f32_e32 v168, v168, v0
	v_pk_mul_f32 v[34:35], v[34:35], v[0:1] op_sel_hi:[1,0]
	v_pk_mul_f32 v[32:33], v[32:33], v[0:1] op_sel_hi:[1,0]
	v_pk_mul_f32 v[30:31], v[30:31], v[0:1] op_sel_hi:[1,0]
	v_pk_mul_f32 v[28:29], v[28:29], v[0:1] op_sel_hi:[1,0]
	v_pk_mul_f32 v[26:27], v[26:27], v[0:1] op_sel_hi:[1,0]
	v_pk_mul_f32 v[24:25], v[24:25], v[0:1] op_sel_hi:[1,0]
	v_pk_mul_f32 v[22:23], v[22:23], v[0:1] op_sel_hi:[1,0]
	v_pk_mul_f32 v[20:21], v[20:21], v[0:1] op_sel_hi:[1,0]
	s_branch .LBB0_1211
.LBB0_1225:
	s_andn2_b64 vcc, exec, s[20:21]
	s_cbranch_vccnz .LBB0_1227
	v_lshlrev_b32_e32 v0, 2, v38
	s_waitcnt lgkmcnt(0)
	v_lshrrev_b32_e32 v2, 1, v38
	v_and_b32_e32 v0, 16, v0
	v_and_b32_e32 v2, 12, v2
	v_and_b32_e32 v3, 35, v38
	v_or3_b32 v0, v0, v3, v2
	v_lshlrev_b32_e32 v2, 7, v0
	v_lshrrev_b32_e32 v0, 1, v0
	s_lshl_b32 s3, s34, 16
	v_xor_b32_e32 v0, v0, v37
	s_and_b32 s3, s3, 0x10000
	v_lshlrev_b32_e32 v0, 4, v0
	s_add_i32 s3, s3, 0
	v_and_b32_e32 v0, 0x70, v0
	v_lshlrev_b32_e32 v3, 7, v38
	v_bitop3_b32 v37, v39, s91, v37 bitop3:0x48
	v_add3_u32 v0, s3, v2, v0
	v_add3_u32 v2, s3, v3, v37
	s_add_i32 s24, s34, 1
	s_cmp_lt_u32 s24, s29
	s_cbranch_scc1 .Lseld_w8
	s_waitcnt vmcnt(0)
	s_branch .Lseld_w
.Lseld_w8:
	s_waitcnt vmcnt(8)
.Lseld_w:
	s_bitcmp1_b32 s34, 0
	s_cbranch_scc1 .Lseld_wrB
	ds_write_b128 v0, v[56:59]
	ds_write_b128 v2, v[60:63] offset:8192
	ds_write_b128 v0, v[64:67] offset:16384
	ds_write_b128 v2, v[68:71] offset:24576
	ds_write_b128 v0, v[72:75] offset:32768
	ds_write_b128 v2, v[76:79] offset:40960
	ds_write_b128 v0, v[80:83] offset:49152
	ds_write_b128 v2, v[84:87] offset:57344
	s_branch .LBB0_1227
.Lseld_wrB:
	ds_write_b128 v0, v[174:177]
	ds_write_b128 v2, v[178:181] offset:8192
	ds_write_b128 v0, v[204:207] offset:16384
	ds_write_b128 v2, v[234:237] offset:24576
	ds_write_b128 v0, v[238:241] offset:32768
	ds_write_b128 v2, v[242:245] offset:40960
	ds_write_b128 v0, v[246:249] offset:49152
	ds_write_b128 v2, v[250:253] offset:57344

; #define LAS __attribute__((address_space(3)))
; __device__ __forceinline__ int launder_v(int x) { asm volatile("" : "+v"(x)); return x; }
; __device__ __forceinline__ int launder_s(int x) { x = __builtin_amdgcn_readfirstlane(x); asm volatile("" : "+s"(x)); return x; }
; __device__ __forceinline__ float col_total(float l) { l += __shfl_xor(l, 16); l += __shfl_xor(l, 32); return l; }
; __device__ __forceinline__ void nsa_block_task(Ctx& C, int task, bf16* ONSA_OUT) {
;     ...
;         stream_tiles<1>(C, src, qb, 1, bufs, [&](const LAS unsigned char* buf, int j) {
;             bf16x8 kf[2][2][2], vf[2][4]; { const int ll = launder_v(lane);
; #pragma unroll
;                 for (int ch = 0; ch < 2; ++ch) { tile_read_k(buf, ch, ll, kf[ch]); tile_read_v(buf, ch, ll, vf[ch]); } }
; #pragma unroll
;             for (int cg = 0; cg < 2; ++cg) { const int tq = tl[cg];
;                 attn_tile64(a[cg], kf, vf, bq[cg], 64 * j, fq, [&](int key) { return key <= tq; }); }
;         });
; #pragma unroll
;         for (int cg = 0; cg < 2; ++cg) { const float lt = col_total(a[cg].l); const float sc = lt > 0.f ? g_s[cg] / lt : 0.f;
; #pragma unroll
;             for (int c = 0; c < 4; ++c) STASH[(cg * 4 + c) * 64 + lane] += a[cg].o[c] * sc; }
;     ...
;         AttnAcc a[2]; attn_init(a[0]); attn_init(a[1]);
;         const int kvw = launder_s(kvh);
;         const TileSrc src{WSP(bf16, WS_KW) + (size_t)kvw * RP * 64, WSP(bf16, WS_VWT) + (size_t)kvw * 64 * RP, RP};
;         const int j0 = qb > 8 ? qb - 8 : 0;
;         const int twmin = t0 + 8 * w, twmax = twmin + 7;
;         stream_tiles<4>(C, src, j0, qb + 1 - j0, bufs, [&](const LAS unsigned char* buf, int j) {
.LBB0_1234:
	v_sub_f32_e32 v88, v88, v169
	v_exp_f32_e32 v88, v88
	v_add_f32_e32 v0, v128, v132
	v_add_f32_e32 v0, 0, v0
	v_add_f32_e32 v2, v129, v133
	v_cndmask_b32_e64 v116, v88, 0, s[28:29]
	v_sub_f32_e32 v88, v93, v169
	v_sub_f32_e32 v92, v92, v169
	v_exp_f32_e32 v88, v88
	v_add_f32_e32 v0, v2, v0
	v_add_f32_e32 v2, v130, v134
	v_exp_f32_e32 v92, v92
	v_add_f32_e32 v0, v2, v0
	v_add_f32_e32 v2, v131, v135
	v_add_f32_e32 v0, v2, v0
	v_add_f32_e32 v2, v146, v147
	v_sub_f32_e32 v89, v89, v169
	v_add_f32_e32 v0, v2, v0
	v_add_f32_e32 v2, v124, v148
	v_exp_f32_e32 v89, v89
	v_cndmask_b32_e64 v119, v88, 0, s[26:27]
	v_sub_f32_e32 v88, v90, v169
	v_add_f32_e32 v0, v2, v0
	v_add_f32_e32 v2, v125, v55
	v_cndmask_b32_e64 v117, v92, 0, s[38:39]
	v_exp_f32_e32 v92, v88
	v_sub_f32_e32 v88, v94, v169
	v_add_f32_e32 v0, v2, v0
	v_add_f32_e32 v2, v54, v126
	v_exp_f32_e32 v93, v88
	v_sub_f32_e32 v88, v91, v169
	v_add_f32_e32 v0, v2, v0
	v_exp_f32_e32 v94, v88
	v_sub_f32_e32 v88, v95, v169
	v_add_f32_e32 v3, v36, v0
	v_sub_f32_e32 v0, v120, v169
	v_sub_f32_e32 v2, v104, v169
	v_sub_f32_e32 v37, v105, v169
	v_sub_f32_e32 v55, v106, v169
	v_sub_f32_e32 v97, v107, v169
	v_cndmask_b32_e64 v118, v89, 0, s[30:31]
	s_barrier
	global_load_dwordx4 v[100:103], v[200:201], off
	global_load_dwordx4 v[104:107], v[200:201], off offset:1024
	global_load_dwordx4 v[108:111], v[200:201], off offset:2048
	v_exp_f32_e32 v95, v88
	global_load_dwordx4 v[88:91], v[200:201], off offset:3072
	v_exp_f32_e32 v0, v0
	v_exp_f32_e32 v2, v2
	v_sub_f32_e32 v36, v121, v169
	v_sub_f32_e32 v96, v123, v169
	v_exp_f32_e32 v36, v36
	v_exp_f32_e32 v37, v37
	v_sub_f32_e32 v54, v122, v169
	v_exp_f32_e32 v96, v96
	v_exp_f32_e32 v54, v54
	v_exp_f32_e32 v55, v55
	v_exp_f32_e32 v97, v97
	v_cndmask_b32_e64 v0, v0, 0, s[44:45]
	v_cndmask_b32_e64 v2, v2, 0, s[16:17]
	v_cndmask_b32_e64 v36, 0, v36, s[46:47]
	v_cndmask_b32_e64 v37, v37, 0, s[48:49]
	v_cndmask_b32_e64 v112, v96, 0, s[36:37]
	v_cvt_pk_bf16_f32 v96, v0, v36
	v_add_f32_e32 v0, v0, v2
	v_cndmask_b32_e64 v54, v54, 0, s[34:35]
	v_cndmask_b32_e64 v55, v55, 0, s[40:41]
	v_cvt_pk_bf16_f32 v98, v2, v37
	v_add_f32_e32 v0, 0, v0
	v_add_f32_e32 v2, v36, v37
	v_cndmask_b32_e64 v113, v97, 0, s[42:43]
	v_add_f32_e32 v0, v2, v0
	v_add_f32_e32 v2, v54, v55
	v_cvt_pk_bf16_f32 v97, v54, v112
	v_cvt_pk_bf16_f32 v99, v55, v113
	v_cndmask_b32_e64 v120, v92, 0, s[18:19]
	v_cndmask_b32_e64 v121, v93, 0, s[22:23]
	v_cndmask_b32_e64 v122, v94, 0, s[20:21]
	v_cndmask_b32_e64 v123, v95, 0, s[24:25]
	v_add_f32_e32 v0, v2, v0
	v_add_f32_e32 v2, v112, v113
	global_load_dwordx4 v[92:95], v[202:203], off
	v_mfma_f32_16x16x32_bf16 v[32:35], v[84:87], v[96:99], v[32:35]
	global_load_dwordx4 v[84:87], v[202:203], off offset:1024
	global_load_dwordx4 v[112:115], v[202:203], off offset:3072
	v_add_f32_e32 v0, v2, v0
	v_mfma_f32_16x16x32_bf16 v[28:31], v[80:83], v[96:99], v[28:31]
	global_load_dwordx4 v[80:83], v[202:203], off offset:2048
	v_add_f32_e32 v2, v116, v117
	v_add_f32_e32 v0, v2, v0
	v_add_f32_e32 v2, v118, v119
	v_add_f32_e32 v0, v2, v0
	v_add_f32_e32 v2, v120, v121
	v_add_f32_e32 v0, v2, v0
	v_add_f32_e32 v2, v122, v123
	v_add_f32_e32 v0, v2, v0
	v_add_f32_e32 v2, v168, v0
	ds_bpermute_b32 v37, v217, v3
	ds_bpermute_b32 v36, v217, v2
	v_mfma_f32_16x16x32_bf16 v[24:27], v[76:79], v[96:99], v[24:27]
	v_cvt_pk_bf16_f32 v76, v116, v118
	v_cvt_pk_bf16_f32 v77, v120, v122
	v_cvt_pk_bf16_f32 v78, v117, v119
	s_waitcnt lgkmcnt(0)
	v_pk_add_f32 v[2:3], v[2:3], v[36:37]
	ds_bpermute_b32 v37, v219, v3
	ds_bpermute_b32 v36, v219, v2
	v_mfma_f32_16x16x32_bf16 v[20:23], v[72:75], v[96:99], v[20:23]
	v_cvt_pk_bf16_f32 v79, v121, v123
	s_waitcnt lgkmcnt(0)
	v_pk_add_f32 v[2:3], v[2:3], v[36:37]
	s_nop 0
	v_div_scale_f32 v0, s[16:17], v3, v3, v187
	v_rcp_f32_e32 v36, v0
	v_mfma_f32_16x16x32_bf16 v[32:35], v[68:71], v[76:79], v[32:35]
	v_fma_f32 v37, -v0, v36, 1.0
	v_fmac_f32_e32 v36, v37, v36
	v_div_scale_f32 v37, vcc, v187, v3, v187
	v_mul_f32_e32 v54, v37, v36
	v_fma_f32 v55, -v0, v54, v37
	v_fmac_f32_e32 v54, v55, v36
	v_fma_f32 v0, -v0, v54, v37
	v_div_fmas_f32 v0, v0, v36, v54
	v_div_fixup_f32 v0, v0, v3, v187
	v_cmp_lt_f32_e32 vcc, 0, v3
	v_div_scale_f32 v3, s[16:17], v2, v2, v183
	v_rcp_f32_e32 v36, v3
	v_cndmask_b32_e32 v0, 0, v0, vcc
	s_waitcnt vmcnt(0)
	v_pk_fma_f32 v[52:53], v[52:53], v[0:1], v[102:103] op_sel_hi:[1,0,1]
	v_pk_fma_f32 v[50:51], v[50:51], v[0:1], v[100:101] op_sel_hi:[1,0,1]
	v_pk_fma_f32 v[48:49], v[48:49], v[0:1], v[106:107] op_sel_hi:[1,0,1]
	v_pk_fma_f32 v[46:47], v[46:47], v[0:1], v[104:105] op_sel_hi:[1,0,1]
	v_pk_fma_f32 v[44:45], v[44:45], v[0:1], v[110:111] op_sel_hi:[1,0,1]
	v_pk_fma_f32 v[42:43], v[42:43], v[0:1], v[108:109] op_sel_hi:[1,0,1]
	v_pk_fma_f32 v[40:41], v[40:41], v[0:1], v[90:91] op_sel_hi:[1,0,1]
	v_pk_fma_f32 v[38:39], v[38:39], v[0:1], v[88:89] op_sel_hi:[1,0,1]
	v_fma_f32 v0, -v3, v36, 1.0
	v_fmac_f32_e32 v36, v0, v36
	v_div_scale_f32 v0, vcc, v183, v2, v183
	v_mul_f32_e32 v37, v0, v36
	global_store_dwordx4 v[200:201], v[38:41], off offset:3072
	v_mfma_f32_16x16x32_bf16 v[28:31], v[64:67], v[76:79], v[28:31]
	global_store_dwordx4 v[200:201], v[50:53], off
	v_fma_f32 v38, -v3, v37, v0
	v_fmac_f32_e32 v37, v38, v36
	v_mfma_f32_16x16x32_bf16 v[24:27], v[60:63], v[76:79], v[24:27]
	v_fma_f32 v0, -v3, v37, v0
	v_div_fmas_f32 v0, v0, v36, v37
	v_div_fixup_f32 v0, v0, v2, v183
	v_mfma_f32_16x16x32_bf16 v[20:23], v[56:59], v[76:79], v[20:23]
	v_cmp_lt_f32_e32 vcc, 0, v2
	global_store_dwordx4 v[200:201], v[46:49], off offset:1024
	global_store_dwordx4 v[200:201], v[42:45], off offset:2048
	v_cndmask_b32_e32 v0, 0, v0, vcc
	v_pk_fma_f32 v[34:35], v[34:35], v[0:1], v[94:95] op_sel_hi:[1,0,1]
	v_pk_fma_f32 v[32:33], v[32:33], v[0:1], v[92:93] op_sel_hi:[1,0,1]
	v_pk_fma_f32 v[30:31], v[30:31], v[0:1], v[86:87] op_sel_hi:[1,0,1]
	v_pk_fma_f32 v[28:29], v[28:29], v[0:1], v[84:85] op_sel_hi:[1,0,1]
	v_pk_fma_f32 v[22:23], v[22:23], v[0:1], v[114:115] op_sel_hi:[1,0,1]
	v_pk_fma_f32 v[20:21], v[20:21], v[0:1], v[112:113] op_sel_hi:[1,0,1]
	v_pk_fma_f32 v[26:27], v[26:27], v[0:1], v[82:83] op_sel_hi:[1,0,1]
	v_pk_fma_f32 v[24:25], v[24:25], v[0:1], v[80:81] op_sel_hi:[1,0,1]
	v_sub_u32_e64 v0, s94, 8 clamp
	global_store_dwordx4 v[202:203], v[32:35], off
	v_readfirstlane_b32 s0, v0
	s_sub_i32 s66, s94, s0
	s_add_i32 s66, s66, 1
	s_cmp_lt_i32 s66, 1
	global_store_dwordx4 v[202:203], v[28:31], off offset:1024
	global_store_dwordx4 v[202:203], v[24:27], off offset:2048
	global_store_dwordx4 v[202:203], v[20:23], off offset:3072
	s_cbranch_scc1 .LBB0_1110
; #define LAS __attribute__((address_space(3)))
; __device__ __forceinline__ int launder_v(int x) { asm volatile("" : "+v"(x)); return x; }
; __device__ __forceinline__ int launder_s(int x) { x = __builtin_amdgcn_readfirstlane(x); asm volatile("" : "+s"(x)); return x; }
; template <int STG, class F>
; __device__ __forceinline__ void stream_tiles(Ctx& C, const TileSrc& src, int tile0, int ntiles, LAS unsigned char* bufs, F&& compute) {
;     ...
;     { const int tidl = launder_v(C.tid);
; #pragma unroll
;       for (int h = 0; h < STG; ++h) { const int t = tile0 + h; tile_fetch(src, 64 * (t < tlast ? t : tlast), tidl, rk[h], rv[h]); }
; #pragma unroll
;       for (int h = 0; h < STG; ++h) tile_store(bufs + h * 16384, tidl, rk[h], rv[h]); }
;     __syncthreads();
; __device__ __forceinline__ void nsa_block_task(Ctx& C, int task, bf16* ONSA_OUT) {
;     ...
;     {
;         AttnAcc a[2]; attn_init(a[0]); attn_init(a[1]);
;         const int kvw = launder_s(kvh);
;         const TileSrc src{WSP(bf16, WS_KW) + (size_t)kvw * RP * 64, WSP(bf16, WS_VWT) + (size_t)kvw * 64 * RP, RP};
;         const int j0 = qb > 8 ? qb - 8 : 0;
;         const int twmin = t0 + 8 * w, twmax = twmin + 7;
;         stream_tiles<4>(C, src, j0, qb + 1 - j0, bufs, [&](const LAS unsigned char* buf, int j) {
	s_mul_hi_i32 s3, s97, 0x208000
	s_mul_i32 s97, s97, 0x208000
	v_readlane_b32 s16, v255, 13
	s_add_u32 s56, s16, s97
	v_readlane_b32 s16, v255, 21
	s_addc_u32 s57, s16, s3
	v_readlane_b32 s16, v255, 23
	s_add_u32 s58, s16, s97
	s_addc_u32 s59, s88, s3
	v_mov_b32_e32 v52, v189
	v_mov_b64_e32 v[20:21], s[58:59]
	v_ashrrev_i32_e32 v53, 3, v52
	v_lshlrev_b32_e32 v54, 4, v52
	v_and_b32_e32 v0, 0x70, v54
	v_mad_i64_i32 v[20:21], s[16:17], v53, s92, v[20:21]
	s_min_i32 s3, s0, s94
	v_lshl_add_u64 v[44:45], v[20:21], 0, v[0:1]
	v_lshl_add_u32 v20, s3, 6, v53
	s_lshl_b32 s50, s3, 7
	s_add_i32 s3, s0, 1
	s_min_i32 s3, s3, s94
	v_lshl_add_u64 v[24:25], v[44:45], 0, s[50:51]
	v_lshl_add_u32 v28, s3, 6, v53
	s_lshl_b32 s50, s3, 7
	s_add_i32 s3, s0, 2
	s_min_i32 s3, s3, s94
	v_lshl_add_u64 v[32:33], v[44:45], 0, s[50:51]
	v_lshl_add_u32 v36, s3, 6, v53
	s_lshl_b32 s50, s3, 7
	s_add_i32 s3, s0, 3
	s_min_i32 s3, s3, s94
	v_lshl_add_u32 v46, s3, 6, v53
	v_ashrrev_i32_e32 v21, 31, v20
	v_ashrrev_i32_e32 v29, 31, v28
	v_ashrrev_i32_e32 v37, 31, v36
	v_ashrrev_i32_e32 v47, 31, v46
	v_lshl_add_u64 v[2:3], s[56:57], 0, v[0:1]
	v_lshlrev_b64 v[20:21], 7, v[20:21]
	v_lshlrev_b64 v[28:29], 7, v[28:29]
	v_lshlrev_b64 v[36:37], 7, v[36:37]
	v_lshl_add_u64 v[40:41], v[44:45], 0, s[50:51]
	v_lshlrev_b64 v[46:47], 7, v[46:47]
	s_lshl_b32 s50, s3, 7
	v_lshl_add_u64 v[20:21], v[2:3], 0, v[20:21]
	v_lshl_add_u64 v[28:29], v[2:3], 0, v[28:29]
	v_lshl_add_u64 v[36:37], v[2:3], 0, v[36:37]
	v_lshl_add_u64 v[2:3], v[2:3], 0, v[46:47]
	v_lshl_add_u64 v[48:49], v[44:45], 0, s[50:51]
	global_load_dwordx4 v[20:23], v[20:21], off
	s_nop 0
	global_load_dwordx4 v[24:27], v[24:25], off
	s_nop 0
	global_load_dwordx4 v[28:31], v[28:29], off
	s_nop 0
	global_load_dwordx4 v[32:35], v[32:33], off
	s_nop 0
	global_load_dwordx4 v[36:39], v[36:37], off
	s_nop 0
	global_load_dwordx4 v[40:43], v[40:41], off
	s_nop 0
	global_load_dwordx4 v[44:47], v[2:3], off
	s_nop 0
	global_load_dwordx4 v[48:51], v[48:49], off
	v_lshlrev_b32_e32 v0, 2, v53
	v_lshrrev_b32_e32 v2, 1, v53
	v_and_b32_e32 v3, 35, v53
	v_and_b32_e32 v0, 16, v0
	v_and_b32_e32 v2, 12, v2
	v_or3_b32 v0, v0, v3, v2
	v_lshlrev_b32_e32 v2, 7, v0
	v_lshrrev_b32_e32 v0, 1, v0
	v_xor_b32_e32 v3, v0, v52
	v_lshlrev_b32_e32 v3, 4, v3
	v_and_b32_e32 v3, 0x70, v3
	v_lshlrev_b32_e32 v53, 7, v53
	v_bitop3_b32 v54, v54, s91, v52 bitop3:0x48
	v_add3_u32 v2, 0, v2, v3
	s_add_i32 s3, s66, 3
	v_add3_u32 v53, 0, v53, v54
	s_min_u32 s16, s94, 8
	v_mov_b32_e32 v3, v1
	s_lshr_b32 s70, s3, 2
	s_lshl_b32 s3, s16, 6
	v_mov_b32_e32 v0, v1
	v_add_u32_e32 v186, 0xfffffe00, v216
	v_add_u32_e32 v187, 0xfffffe04, v216
	s_mov_b32 s67, 0
	s_add_i32 s68, s95, 0xfffffe00
	s_add_i32 s69, s95, 0xfffffe07
	s_sub_i32 s71, s54, s3
	v_subrev_u32_e32 v233, s3, v136
	v_mov_b32_e32 v235, 0xf149f2ca
	v_mov_b32_e32 v238, 0
	s_mov_b64 s[54:55], 0
	v_mov_b32_e32 v68, 0
	v_mov_b32_e32 v234, 0
	v_mov_b32_e32 v236, 0
	v_mov_b32_e32 v237, 0xf149f2ca
	s_mov_b32 s84, 0
	s_waitcnt vmcnt(0) lgkmcnt(0)
	ds_write_b128 v2, v[20:23]
	ds_write_b128 v53, v[24:27] offset:8192
	ds_write_b128 v2, v[28:31] offset:16384
	ds_write_b128 v53, v[32:35] offset:24576
	ds_write_b128 v2, v[36:39] offset:32768
	ds_write_b128 v53, v[40:43] offset:40960
	ds_write_b128 v2, v[44:47] offset:49152
	ds_write_b128 v53, v[48:51] offset:57344
	v_mov_b32_e32 v2, v1
	v_mov_b64_e32 v[182:183], v[2:3]
	v_mov_b64_e32 v[170:171], v[2:3]
	v_mov_b64_e32 v[174:175], v[2:3]
	v_mov_b64_e32 v[178:179], v[2:3]
	v_mov_b64_e32 v[86:87], v[2:3]
	v_mov_b64_e32 v[74:75], v[2:3]
	v_mov_b64_e32 v[78:79], v[2:3]
	v_mov_b64_e32 v[82:83], v[2:3]
	v_mov_b64_e32 v[54:55], v[2:3]
	v_mov_b64_e32 v[58:59], v[2:3]
	v_mov_b64_e32 v[62:63], v[2:3]
	v_mov_b64_e32 v[66:67], v[2:3]
	v_mov_b64_e32 v[90:91], v[2:3]
	v_mov_b64_e32 v[94:95], v[2:3]
	v_mov_b64_e32 v[98:99], v[2:3]
	v_mov_b64_e32 v[102:103], v[2:3]
	v_mov_b64_e32 v[180:181], v[0:1]
	v_mov_b64_e32 v[168:169], v[0:1]
	v_mov_b64_e32 v[172:173], v[0:1]
	v_mov_b64_e32 v[176:177], v[0:1]
	v_mov_b64_e32 v[84:85], v[0:1]
	v_mov_b64_e32 v[72:73], v[0:1]
	v_mov_b64_e32 v[76:77], v[0:1]
	v_mov_b64_e32 v[80:81], v[0:1]
	v_mov_b64_e32 v[52:53], v[0:1]
	v_mov_b64_e32 v[56:57], v[0:1]
	v_mov_b64_e32 v[60:61], v[0:1]
	v_mov_b64_e32 v[64:65], v[0:1]
	v_mov_b64_e32 v[88:89], v[0:1]
	v_mov_b64_e32 v[92:93], v[0:1]
	v_mov_b64_e32 v[96:97], v[0:1]
	v_mov_b64_e32 v[100:101], v[0:1]
	s_waitcnt lgkmcnt(0)
	s_barrier
	s_branch .LBB0_1237
